# attention steady loop: no instructions left between the last score MFMA and the first P.V MFMA (tail adds/packs and the LDS-DMA issues follow the first P.V MFMA)
# baseline (speedup 1.0000x reference)
.LBB0_310:
	s_lshl_b32 s14, s14, 1
	v_add_u32_e32 v217, s14, v244
	ds_read_b64_tr_b16 v[208:209], v217 offset:24576
	ds_read_b64_tr_b16 v[210:211], v217 offset:25088
	v_mfma_f32_32x32x16_bf16 v[128:143], v[204:207], v[172:175], v[64:79]
	v_add_f32_e32 v112, v96, v97
	v_add_f32_e32 v112, v98, v112
	v_add_f32_e32 v112, v99, v112
	v_add_f32_e32 v112, v100, v112
	v_add_f32_e32 v112, v101, v112
	v_cvt_pk_bf16_f32 v164, v96, v97
	v_cvt_pk_bf16_f32 v165, v98, v99
	ds_read_b64_tr_b16 v[96:97], v217 offset:28672
	ds_read_b64_tr_b16 v[98:99], v217 offset:29184
	v_add_f32_e32 v112, v102, v112
	v_add_f32_e32 v112, v103, v112
	v_add_f32_e32 v112, v104, v112
	v_add_f32_e32 v144, v105, v112
	v_mfma_f32_32x32x16_bf16 v[112:127], v[200:203], v[172:175], v[64:79]
	v_cvt_pk_bf16_f32 v166, v100, v101
	v_cvt_pk_bf16_f32 v167, v102, v103
	ds_read_b64_tr_b16 v[100:101], v217 offset:25600
	ds_read_b64_tr_b16 v[102:103], v217 offset:26112
	v_mfma_f32_32x32x16_bf16 v[128:143], v[196:199], v[168:171], v[128:143]
	v_add_f32_e32 v144, v106, v144
	v_add_f32_e32 v144, v107, v144
	v_add_f32_e32 v144, v108, v144
	v_add_f32_e32 v144, v109, v144
	v_cvt_pk_bf16_f32 v156, v104, v105
	v_cvt_pk_bf16_f32 v157, v106, v107
	ds_read_b64_tr_b16 v[104:105], v217 offset:29696
	ds_read_b64_tr_b16 v[106:107], v217 offset:30208
	v_mfma_f32_32x32x16_bf16 v[112:127], v[192:195], v[168:171], v[112:127]
	v_add_f32_e32 v144, v110, v144
	v_add_f32_e32 v144, v111, v144
	v_add_f32_e32 v144, v80, v144
	v_add_f32_e32 v144, v81, v144
	v_cvt_pk_bf16_f32 v158, v108, v109
	v_cvt_pk_bf16_f32 v159, v110, v111
	ds_read_b64_tr_b16 v[108:109], v217 offset:26624
	ds_read_b64_tr_b16 v[110:111], v217 offset:27136
	v_mfma_f32_32x32x16_bf16 v[128:143], v[188:191], v[160:163], v[128:143]
	v_add_f32_e32 v144, v82, v144
	v_add_f32_e32 v144, v83, v144
	v_add_f32_e32 v144, v84, v144
	v_add_f32_e32 v144, v85, v144
	v_cvt_pk_bf16_f32 v148, v80, v81
	v_cvt_pk_bf16_f32 v149, v82, v83
	ds_read_b64_tr_b16 v[80:81], v217 offset:30720
	ds_read_b64_tr_b16 v[82:83], v217 offset:31232
	v_mfma_f32_32x32x16_bf16 v[112:127], v[184:187], v[160:163], v[112:127]
	v_add_f32_e32 v144, v86, v144
	v_add_f32_e32 v144, v87, v144
	v_add_f32_e32 v144, v88, v144
	v_add_f32_e32 v144, v89, v144
	v_cvt_pk_bf16_f32 v150, v84, v85
	v_cvt_pk_bf16_f32 v151, v86, v87
	ds_read_b64_tr_b16 v[84:85], v217 offset:27648
	ds_read_b64_tr_b16 v[86:87], v217 offset:28160
	v_mfma_f32_32x32x16_bf16 v[128:143], v[180:183], v[152:155], v[128:143]
	v_add_f32_e32 v144, v90, v144
	v_add_f32_e32 v144, v91, v144
	v_add_f32_e32 v144, v92, v144
	v_add_f32_e32 v180, v93, v144
	v_cvt_pk_bf16_f32 v144, v88, v89
	v_cvt_pk_bf16_f32 v145, v90, v91
	ds_read_b64_tr_b16 v[88:89], v217 offset:31744
	ds_read_b64_tr_b16 v[90:91], v217 offset:32256
	v_mfma_f32_32x32x16_bf16 v[112:127], v[176:179], v[152:155], v[112:127]
	s_waitcnt lgkmcnt(12)
	v_mfma_f32_32x32x16_bf16 v[32:47], v[164:167], v[208:211], v[32:47]
	v_add_f32_e32 v146, v94, v180
	v_add_f32_e32 v176, v95, v146
	v_cvt_pk_bf16_f32 v146, v92, v93
	v_cvt_pk_bf16_f32 v147, v94, v95
	s_add_i32 m0, s24, s63
	s_mov_b32 s14, s32
	s_mov_b32 s15, s70
	global_load_lds_dwordx4 v212, s[14:15]
	s_lshl_b32 s14, s22, 1
	s_add_i32 s14, s14, s64
	s_mov_b32 m0, s14
	s_add_i32 s14, s14, 0x1f80
	global_load_lds_dwordx4 v226, s[98:99]
	s_mov_b32 m0, s14
	s_nop 0
	global_load_lds_dwordx4 v226, s[98:99] offset:128
	ds_read_b64_tr_b16 v[92:93], v217 offset:32768
	ds_read_b64_tr_b16 v[94:95], v217 offset:33280
	v_mfma_f32_32x32x16_bf16 v[48:63], v[164:167], v[96:99], v[48:63]
	v_max_f32_e32 v222, v128, v129
	v_max3_f32 v223, v130, v131, v113
	v_max3_f32 v222, v222, v112, v114
	v_max3_f32 v222, v222, v115, v132
	ds_read_b64_tr_b16 v[96:97], v217 offset:36864
	ds_read_b64_tr_b16 v[98:99], v217 offset:37376
	s_waitcnt lgkmcnt(12)
	v_mfma_f32_32x32x16_bf16 v[32:47], v[156:159], v[100:103], v[32:47]
	v_max3_f32 v223, v223, v134, v135
	v_max3_f32 v222, v222, v133, v116
	v_max3_f32 v223, v223, v118, v119
	v_max3_f32 v222, v222, v117, v136
	ds_read_b64_tr_b16 v[100:101], v217 offset:33792
	ds_read_b64_tr_b16 v[102:103], v217 offset:34304
	v_mfma_f32_32x32x16_bf16 v[48:63], v[156:159], v[104:107], v[48:63]
	v_max3_f32 v223, v223, v138, v139
	v_max3_f32 v222, v222, v137, v120
	v_max3_f32 v223, v223, v122, v123
	v_max3_f32 v222, v222, v121, v140
	ds_read_b64_tr_b16 v[104:105], v217 offset:37888
	ds_read_b64_tr_b16 v[106:107], v217 offset:38400
	s_waitcnt lgkmcnt(12)
	v_mfma_f32_32x32x16_bf16 v[32:47], v[148:151], v[108:111], v[32:47]
	v_max3_f32 v223, v223, v142, v143
	v_max3_f32 v222, v222, v141, v124
	v_max3_f32 v223, v223, v126, v127
	v_max3_f32 v222, v222, v125, v223
	ds_read_b64_tr_b16 v[108:109], v217 offset:34816
	ds_read_b64_tr_b16 v[110:111], v217 offset:35328
	v_mfma_f32_32x32x16_bf16 v[48:63], v[148:151], v[80:83], v[48:63]
	v_mov_b32_e32 v223, v222
	v_add_f32_e32 v215, v249, v176
	s_nop 0
	v_permlane32_swap_b32_e32 v222, v223
	v_max_f32_e32 v222, v222, v223
	v_cmp_lt_f32_e32 vcc, s33, v222
	s_nop 0
	s_mov_b64 s[20:21], vcc
	s_cbranch_vccnz .LBB0_318
.LBB0_311:
	v_exp_f32_e32 v128, v128
	v_exp_f32_e32 v129, v129
	ds_read_b64_tr_b16 v[188:189], v217 offset:38912
	ds_read_b64_tr_b16 v[190:191], v217 offset:39424
	s_waitcnt lgkmcnt(12)
	v_mfma_f32_32x32x16_bf16 v[32:47], v[144:147], v[84:87], v[32:47]
	v_exp_f32_e32 v130, v130
	v_exp_f32_e32 v131, v131
	v_exp_f32_e32 v132, v132
	ds_read_b64_tr_b16 v[84:85], v217 offset:35840
	ds_read_b64_tr_b16 v[86:87], v217 offset:36352
	v_mfma_f32_32x32x16_bf16 v[48:63], v[144:147], v[88:91], v[48:63]
	v_exp_f32_e32 v133, v133
	v_exp_f32_e32 v134, v134
	v_exp_f32_e32 v135, v135
	ds_read_b64_tr_b16 v[88:89], v217 offset:39936
	ds_read_b64_tr_b16 v[90:91], v217 offset:40448
	s_waitcnt lgkmcnt(12)
	v_mfma_f32_32x32x16_bf16 v[16:31], v[164:167], v[92:95], v[16:31]
	v_exp_f32_e32 v136, v136
	v_exp_f32_e32 v137, v137
	v_exp_f32_e32 v138, v138
	v_add_u32_e32 v92, s22, v247
	ds_read_b128 v[80:83], v92
	ds_read_b128 v[200:203], v92 offset:512
	v_mfma_f32_32x32x16_bf16 v[0:15], v[164:167], v[96:99], v[0:15]
	v_exp_f32_e32 v139, v139
	v_exp_f32_e32 v140, v140
	v_exp_f32_e32 v141, v141
	ds_read_b128 v[204:207], v92 offset:2048
	ds_read_b128 v[196:199], v92 offset:2560
	s_waitcnt lgkmcnt(12)
	v_mfma_f32_32x32x16_bf16 v[16:31], v[156:159], v[100:103], v[16:31]
	v_exp_f32_e32 v142, v142
	v_exp_f32_e32 v143, v143
	v_exp_f32_e32 v112, v112
	ds_read_b128 v[192:195], v92 offset:4096
	ds_read_b128 v[184:187], v92 offset:4608
	v_mfma_f32_32x32x16_bf16 v[0:15], v[156:159], v[104:107], v[0:15]
	v_exp_f32_e32 v113, v113
	v_exp_f32_e32 v114, v114
	v_exp_f32_e32 v115, v115
	ds_read_b128 v[180:183], v92 offset:6144
	ds_read_b128 v[176:179], v92 offset:6656
	s_waitcnt lgkmcnt(12)
	v_mfma_f32_32x32x16_bf16 v[16:31], v[148:151], v[108:111], v[16:31]
	v_exp_f32_e32 v116, v116
	v_exp_f32_e32 v117, v117
	v_exp_f32_e32 v118, v118
	v_mfma_f32_32x32x16_bf16 v[0:15], v[148:151], v[188:191], v[0:15]
	v_exp_f32_e32 v119, v119
	v_exp_f32_e32 v120, v120
	v_exp_f32_e32 v121, v121
	s_waitcnt lgkmcnt(8)
	v_mfma_f32_32x32x16_bf16 v[16:31], v[144:147], v[84:87], v[16:31]
	v_exp_f32_e32 v122, v122
	v_exp_f32_e32 v123, v123
	v_exp_f32_e32 v124, v124
	v_mfma_f32_32x32x16_bf16 v[0:15], v[144:147], v[88:91], v[0:15]
	v_exp_f32_e32 v125, v125
	v_exp_f32_e32 v126, v126
	v_exp_f32_e32 v127, v127
	s_waitcnt vmcnt(3) lgkmcnt(0)
	s_barrier
	s_cmp_eq_u64 s[20:21], 0
	s_cbranch_scc1 .LBB0_313
	s_waitcnt lgkmcnt(0)
	v_add_u32_e32 v208, s65, v248
	ds_read_b128 v[84:87], v208 offset:96
	ds_read_b128 v[88:91], v208 offset:64
	ds_read_b128 v[92:95], v208 offset:32
	ds_read_b128 v[96:99], v208
	s_waitcnt lgkmcnt(3)
	v_pk_mul_f32 v[44:45], v[44:45], v[84:85]
	s_waitcnt lgkmcnt(2)
	v_pk_mul_f32 v[40:41], v[40:41], v[88:89]
	s_waitcnt lgkmcnt(1)
	v_pk_mul_f32 v[36:37], v[36:37], v[92:93]
	v_pk_mul_f32 v[46:47], v[46:47], v[86:87]
	v_pk_mul_f32 v[42:43], v[42:43], v[90:91]
	v_pk_mul_f32 v[38:39], v[38:39], v[94:95]
	s_waitcnt lgkmcnt(0)
	v_pk_mul_f32 v[34:35], v[34:35], v[98:99]
	v_pk_mul_f32 v[32:33], v[32:33], v[96:97]
	v_pk_mul_f32 v[60:61], v[60:61], v[84:85]
	v_pk_mul_f32 v[56:57], v[56:57], v[88:89]
	v_pk_mul_f32 v[52:53], v[52:53], v[92:93]
	v_pk_mul_f32 v[62:63], v[62:63], v[86:87]
	v_pk_mul_f32 v[58:59], v[58:59], v[90:91]
	v_pk_mul_f32 v[54:55], v[54:55], v[94:95]
	v_pk_mul_f32 v[50:51], v[50:51], v[98:99]
	v_pk_mul_f32 v[48:49], v[48:49], v[96:97]
	v_pk_mul_f32 v[28:29], v[28:29], v[84:85]
	v_pk_mul_f32 v[24:25], v[24:25], v[88:89]
	v_pk_mul_f32 v[20:21], v[20:21], v[92:93]
	v_pk_mul_f32 v[30:31], v[30:31], v[86:87]
	v_pk_mul_f32 v[26:27], v[26:27], v[90:91]
	v_pk_mul_f32 v[22:23], v[22:23], v[94:95]
	v_pk_mul_f32 v[18:19], v[18:19], v[98:99]
	v_pk_mul_f32 v[16:17], v[16:17], v[96:97]
	v_pk_mul_f32 v[12:13], v[12:13], v[84:85]
	v_pk_mul_f32 v[8:9], v[8:9], v[88:89]
	v_pk_mul_f32 v[4:5], v[4:5], v[92:93]
	v_pk_mul_f32 v[14:15], v[14:15], v[86:87]
	v_pk_mul_f32 v[10:11], v[10:11], v[90:91]
	v_pk_mul_f32 v[6:7], v[6:7], v[94:95]
	v_pk_mul_f32 v[2:3], v[2:3], v[98:99]
	v_pk_mul_f32 v[0:1], v[0:1], v[96:97]
.LBB0_313:
	s_add_i32 s14, s22, 0x2000
	s_cmpk_lg_i32 s22, 0x4000
	s_cselect_b32 s66, s14, 0
	s_lshl_b32 s14, s24, 1
	v_add_u32_e32 v209, s14, v244
	ds_read_b64_tr_b16 v[188:189], v209 offset:24576
	ds_read_b64_tr_b16 v[190:191], v209 offset:25088
	v_mfma_f32_32x32x16_bf16 v[96:111], v[80:83], v[172:175], v[64:79]
	v_add_f32_e32 v84, v128, v129
	v_add_f32_e32 v84, v130, v84
	v_add_f32_e32 v84, v131, v84
	v_add_f32_e32 v84, v132, v84
	v_add_f32_e32 v84, v133, v84
	v_cvt_pk_bf16_f32 v164, v128, v129
	v_cvt_pk_bf16_f32 v165, v130, v131
	ds_read_b64_tr_b16 v[128:129], v209 offset:28672
	ds_read_b64_tr_b16 v[130:131], v209 offset:29184
	v_add_f32_e32 v80, v134, v84
	v_add_f32_e32 v80, v135, v80
	v_add_f32_e32 v80, v136, v80
	v_add_f32_e32 v144, v137, v80
	v_mfma_f32_32x32x16_bf16 v[80:95], v[200:203], v[172:175], v[64:79]
	v_cvt_pk_bf16_f32 v166, v132, v133
	v_cvt_pk_bf16_f32 v167, v134, v135
	ds_read_b64_tr_b16 v[132:133], v209 offset:25600
	ds_read_b64_tr_b16 v[134:135], v209 offset:26112
	v_mfma_f32_32x32x16_bf16 v[96:111], v[204:207], v[168:171], v[96:111]
	v_add_f32_e32 v144, v138, v144
	v_add_f32_e32 v144, v139, v144
	v_add_f32_e32 v144, v140, v144
	v_add_f32_e32 v144, v141, v144
	v_cvt_pk_bf16_f32 v156, v136, v137
	v_cvt_pk_bf16_f32 v157, v138, v139
	ds_read_b64_tr_b16 v[136:137], v209 offset:29696
	ds_read_b64_tr_b16 v[138:139], v209 offset:30208
	v_mfma_f32_32x32x16_bf16 v[80:95], v[196:199], v[168:171], v[80:95]
	v_add_f32_e32 v144, v142, v144
	v_add_f32_e32 v144, v143, v144
	v_add_f32_e32 v144, v112, v144
	v_add_f32_e32 v144, v113, v144
	v_cvt_pk_bf16_f32 v158, v140, v141
	v_cvt_pk_bf16_f32 v159, v142, v143
	ds_read_b64_tr_b16 v[140:141], v209 offset:26624
	ds_read_b64_tr_b16 v[142:143], v209 offset:27136
	v_mfma_f32_32x32x16_bf16 v[96:111], v[192:195], v[160:163], v[96:111]
	v_add_f32_e32 v144, v114, v144
	v_add_f32_e32 v144, v115, v144
	v_add_f32_e32 v144, v116, v144
	v_add_f32_e32 v144, v117, v144
	v_cvt_pk_bf16_f32 v148, v112, v113
	v_cvt_pk_bf16_f32 v149, v114, v115
	ds_read_b64_tr_b16 v[112:113], v209 offset:30720
	ds_read_b64_tr_b16 v[114:115], v209 offset:31232
	v_mfma_f32_32x32x16_bf16 v[80:95], v[184:187], v[160:163], v[80:95]
	v_add_f32_e32 v144, v118, v144
	v_add_f32_e32 v144, v119, v144
	v_add_f32_e32 v144, v120, v144
	v_add_f32_e32 v144, v121, v144
	v_cvt_pk_bf16_f32 v150, v116, v117
	v_cvt_pk_bf16_f32 v151, v118, v119
	ds_read_b64_tr_b16 v[116:117], v209 offset:27648
	ds_read_b64_tr_b16 v[118:119], v209 offset:28160
	v_mfma_f32_32x32x16_bf16 v[96:111], v[180:183], v[152:155], v[96:111]
	v_add_f32_e32 v144, v122, v144
	v_add_f32_e32 v144, v123, v144
	v_add_f32_e32 v144, v124, v144
	v_add_f32_e32 v180, v125, v144
	v_cvt_pk_bf16_f32 v144, v120, v121
	v_cvt_pk_bf16_f32 v145, v122, v123
	ds_read_b64_tr_b16 v[120:121], v209 offset:31744
	ds_read_b64_tr_b16 v[122:123], v209 offset:32256
	v_mfma_f32_32x32x16_bf16 v[80:95], v[176:179], v[152:155], v[80:95]
	s_waitcnt lgkmcnt(12)
	v_mfma_f32_32x32x16_bf16 v[32:47], v[164:167], v[188:191], v[32:47]
	v_add_f32_e32 v146, v126, v180
	v_add_f32_e32 v176, v127, v146
	v_cvt_pk_bf16_f32 v146, v124, v125
	v_cvt_pk_bf16_f32 v147, v126, v127
	s_add_i32 m0, s22, s63
	s_add_u32 s14, s32, 0x20000
	s_addc_u32 s15, s70, 0
	global_load_lds_dwordx4 v212, s[14:15]
	s_lshl_b32 s20, s66, 1
	s_add_i32 s20, s20, s64
	s_add_u32 s14, s98, 0x20000
	s_addc_u32 s15, s99, 0
	s_mov_b32 m0, s20
	s_add_i32 s20, s20, 0x1f80
	global_load_lds_dwordx4 v226, s[14:15]
	s_mov_b32 m0, s20
	s_nop 0
	global_load_lds_dwordx4 v226, s[14:15] offset:128
	ds_read_b64_tr_b16 v[124:125], v209 offset:32768
	ds_read_b64_tr_b16 v[126:127], v209 offset:33280
	v_mfma_f32_32x32x16_bf16 v[48:63], v[164:167], v[128:131], v[48:63]
	v_max_f32_e32 v224, v96, v97
	v_max3_f32 v225, v98, v99, v81
	v_max3_f32 v224, v224, v80, v82
	v_max3_f32 v224, v224, v83, v100
	ds_read_b64_tr_b16 v[128:129], v209 offset:36864
	ds_read_b64_tr_b16 v[130:131], v209 offset:37376
	s_waitcnt lgkmcnt(12)
	v_mfma_f32_32x32x16_bf16 v[32:47], v[156:159], v[132:135], v[32:47]
	v_max3_f32 v225, v225, v102, v103
	v_max3_f32 v224, v224, v101, v84
	v_max3_f32 v225, v225, v86, v87
	v_max3_f32 v224, v224, v85, v104
	ds_read_b64_tr_b16 v[132:133], v209 offset:33792
	ds_read_b64_tr_b16 v[134:135], v209 offset:34304
	v_mfma_f32_32x32x16_bf16 v[48:63], v[156:159], v[136:139], v[48:63]
	v_max3_f32 v225, v225, v106, v107
	v_max3_f32 v224, v224, v105, v88
	v_max3_f32 v225, v225, v90, v91
	v_max3_f32 v224, v224, v89, v108
	ds_read_b64_tr_b16 v[136:137], v209 offset:37888
	ds_read_b64_tr_b16 v[138:139], v209 offset:38400
	s_waitcnt lgkmcnt(12)
	v_mfma_f32_32x32x16_bf16 v[32:47], v[148:151], v[140:143], v[32:47]
	v_max3_f32 v225, v225, v110, v111
	v_max3_f32 v224, v224, v109, v92
	v_max3_f32 v225, v225, v94, v95
	v_max3_f32 v224, v224, v93, v225
	ds_read_b64_tr_b16 v[140:141], v209 offset:34816
	ds_read_b64_tr_b16 v[142:143], v209 offset:35328
	v_mfma_f32_32x32x16_bf16 v[48:63], v[148:151], v[112:115], v[48:63]
	v_mov_b32_e32 v225, v224
	v_add_f32_e32 v249, v215, v176
	s_nop 0
	v_permlane32_swap_b32_e32 v224, v225
	v_max_f32_e32 v224, v224, v225
	v_cmp_lt_f32_e32 vcc, s33, v224
	s_nop 0
	s_mov_b64 s[20:21], vcc
	s_cbranch_vccnz .LBB0_321
.LBB0_314:
	v_exp_f32_e32 v96, v96
	v_exp_f32_e32 v97, v97
	ds_read_b64_tr_b16 v[112:113], v209 offset:38912
	ds_read_b64_tr_b16 v[114:115], v209 offset:39424
	s_waitcnt lgkmcnt(12)
	v_mfma_f32_32x32x16_bf16 v[32:47], v[144:147], v[116:119], v[32:47]
	v_exp_f32_e32 v98, v98
	v_exp_f32_e32 v99, v99
	v_exp_f32_e32 v100, v100
	ds_read_b64_tr_b16 v[116:117], v209 offset:35840
	ds_read_b64_tr_b16 v[118:119], v209 offset:36352
	v_mfma_f32_32x32x16_bf16 v[48:63], v[144:147], v[120:123], v[48:63]
	v_exp_f32_e32 v101, v101
	v_exp_f32_e32 v102, v102
	v_exp_f32_e32 v103, v103
	ds_read_b64_tr_b16 v[120:121], v209 offset:39936
	ds_read_b64_tr_b16 v[122:123], v209 offset:40448
	s_waitcnt lgkmcnt(12)
	v_mfma_f32_32x32x16_bf16 v[16:31], v[164:167], v[124:127], v[16:31]
	v_exp_f32_e32 v104, v104
	v_exp_f32_e32 v105, v105
	v_exp_f32_e32 v106, v106
	v_add_u32_e32 v124, s66, v247
	ds_read_b128 v[204:207], v124
	ds_read_b128 v[200:203], v124 offset:512
	v_mfma_f32_32x32x16_bf16 v[0:15], v[164:167], v[128:131], v[0:15]
	v_exp_f32_e32 v107, v107
	v_exp_f32_e32 v108, v108
	v_exp_f32_e32 v109, v109
	ds_read_b128 v[196:199], v124 offset:2048
	ds_read_b128 v[192:195], v124 offset:2560
	s_waitcnt lgkmcnt(12)
	v_mfma_f32_32x32x16_bf16 v[16:31], v[156:159], v[132:135], v[16:31]
	v_exp_f32_e32 v110, v110
	v_exp_f32_e32 v111, v111
	v_exp_f32_e32 v80, v80
	ds_read_b128 v[188:191], v124 offset:4096
	ds_read_b128 v[184:187], v124 offset:4608
	v_mfma_f32_32x32x16_bf16 v[0:15], v[156:159], v[136:139], v[0:15]
	v_exp_f32_e32 v81, v81
	v_exp_f32_e32 v82, v82
	v_exp_f32_e32 v83, v83
	ds_read_b128 v[180:183], v124 offset:6144
	ds_read_b128 v[176:179], v124 offset:6656
	s_waitcnt lgkmcnt(12)
	v_mfma_f32_32x32x16_bf16 v[16:31], v[148:151], v[140:143], v[16:31]
	v_exp_f32_e32 v84, v84
	v_exp_f32_e32 v85, v85
	v_exp_f32_e32 v86, v86
	v_mfma_f32_32x32x16_bf16 v[0:15], v[148:151], v[112:115], v[0:15]
	v_exp_f32_e32 v87, v87
	v_exp_f32_e32 v88, v88
	v_exp_f32_e32 v89, v89
	s_waitcnt lgkmcnt(8)
	v_mfma_f32_32x32x16_bf16 v[16:31], v[144:147], v[116:119], v[16:31]
	v_exp_f32_e32 v90, v90
	v_exp_f32_e32 v91, v91
	v_exp_f32_e32 v92, v92
	v_mfma_f32_32x32x16_bf16 v[0:15], v[144:147], v[120:123], v[0:15]
	v_exp_f32_e32 v93, v93
	v_exp_f32_e32 v94, v94
	v_exp_f32_e32 v95, v95
	s_waitcnt vmcnt(3) lgkmcnt(0)
	s_barrier
	s_cmp_eq_u64 s[20:21], 0
	s_cbranch_scc1 .LBB0_316
	s_waitcnt lgkmcnt(0)
	v_add_u32_e32 v208, s65, v248
	ds_read_b128 v[112:115], v208 offset:96
	ds_read_b128 v[116:119], v208 offset:64
	ds_read_b128 v[120:123], v208 offset:32
	ds_read_b128 v[124:127], v208
	s_waitcnt lgkmcnt(3)
	v_pk_mul_f32 v[44:45], v[44:45], v[112:113]
	s_waitcnt lgkmcnt(2)
	v_pk_mul_f32 v[40:41], v[40:41], v[116:117]
	s_waitcnt lgkmcnt(1)
	v_pk_mul_f32 v[36:37], v[36:37], v[120:121]
	v_pk_mul_f32 v[46:47], v[46:47], v[114:115]
	v_pk_mul_f32 v[42:43], v[42:43], v[118:119]
	v_pk_mul_f32 v[38:39], v[38:39], v[122:123]
	s_waitcnt lgkmcnt(0)
	v_pk_mul_f32 v[34:35], v[34:35], v[126:127]
	v_pk_mul_f32 v[32:33], v[32:33], v[124:125]
	v_pk_mul_f32 v[60:61], v[60:61], v[112:113]
	v_pk_mul_f32 v[56:57], v[56:57], v[116:117]
	v_pk_mul_f32 v[52:53], v[52:53], v[120:121]
	v_pk_mul_f32 v[62:63], v[62:63], v[114:115]
	v_pk_mul_f32 v[58:59], v[58:59], v[118:119]
	v_pk_mul_f32 v[54:55], v[54:55], v[122:123]
	v_pk_mul_f32 v[50:51], v[50:51], v[126:127]
	v_pk_mul_f32 v[48:49], v[48:49], v[124:125]
	v_pk_mul_f32 v[28:29], v[28:29], v[112:113]
	v_pk_mul_f32 v[24:25], v[24:25], v[116:117]
	v_pk_mul_f32 v[20:21], v[20:21], v[120:121]
	v_pk_mul_f32 v[30:31], v[30:31], v[114:115]
	v_pk_mul_f32 v[26:27], v[26:27], v[118:119]
	v_pk_mul_f32 v[22:23], v[22:23], v[122:123]
	v_pk_mul_f32 v[18:19], v[18:19], v[126:127]
	v_pk_mul_f32 v[16:17], v[16:17], v[124:125]
	v_pk_mul_f32 v[12:13], v[12:13], v[112:113]
	v_pk_mul_f32 v[8:9], v[8:9], v[116:117]
	v_pk_mul_f32 v[4:5], v[4:5], v[120:121]
	v_pk_mul_f32 v[14:15], v[14:15], v[114:115]
	v_pk_mul_f32 v[10:11], v[10:11], v[118:119]
	v_pk_mul_f32 v[6:7], v[6:7], v[122:123]
	v_pk_mul_f32 v[2:3], v[2:3], v[126:127]
	v_pk_mul_f32 v[0:1], v[0:1], v[124:125]
